# FFN-up GEMM epilogue: lanes transposed with ds_bpermute before the bf16 stores so 4 consecutive lanes write 64 contiguous bytes of one row
# speedup vs baseline: 1.0356x; 1.0112x over previous
; #define PG8_STAGE(bufoff, gbase, voff) do { _Pragma("unroll") for (int _i = 0; _i < 2; ++_i) \
;         __builtin_amdgcn_global_load_lds((const unsigned*)((const char*)(gbase) + (voff)[_i]), (PG8_LAS unsigned*)(lds + (bufoff) + ldsw + _i * 8192), 16, 0, 0); } while (0)
; #define PG8_WAIT_V(n) asm volatile("s_waitcnt vmcnt(" #n ")" ::: "memory")
; #define PG8_BAR __builtin_amdgcn_s_barrier()
; template <class Epi, class Sched, bool ALIGN_EPI = false, bool SP2 = false>
; __device__ __forceinline__ void gemm_phase(PG8_LAS unsigned char* lds, const Gemm g, const Sched& S, const Epi& E) {
;     ...
;         PG8_STAGE(PG8_SB(0, 0), cB, voffB); PG8_STAGE(PG8_SB(0, 1), cB + hstep, voffB); PG8_STAGE(PG8_SA(0, 0), cA, voffA); PG8_STAGE(PG8_SA(0, 1), cA + hstep, voffA);
;         if (wr == 1) PG8_BAR;
;         PG8_WAIT_V(2); PG8_BAR;
;         PG8_STAGE(PG8_SB(1, 0), cB + kstep, voffB); PG8_STAGE(PG8_SA(1, 0), cA + kstep, voffA); PG8_STAGE(PG8_SB(1, 1), cB + hstep + kstep, voffB);
;         PG8_WAIT_V(6); PG8_BAR;
;     DI void operator()(const f32x4 (&acc)[2][2][4][2], const Unit& u, int wr, int wc, int fr, int fq) const {
;     ...
;                 const int r = u.pm * BM + ai * HALF + wr * 64 + m * 16 + fr;
; #pragma unroll
;                 for (int bj = 0; bj < 2; ++bj) f(r, u.pn * BM + bj * HALF + wc * 32 + 8 * fq, acc[ai][bj][m][0], acc[ai][bj][m][1]);
.LBB0_733:
	s_lshl_b32 s9, s16, 5
	s_mov_b64 s[16:17], 0x80
	s_add_i32 m0, s45, 0x18000
	v_lshl_add_u64 v[6:7], v[6:7], 0, s[16:17]
	s_lshl_b32 s5, s19, 13
	s_and_b32 s9, s9, 0x60
	s_waitcnt vmcnt(2)
	s_barrier
	global_load_lds_dwordx4 v[6:7], off
	v_lshl_add_u64 v[4:5], v[4:5], 0, s[16:17]
	s_add_i32 m0, s45, 0x1a000
	s_add_i32 s61, s45, 0x8000
	s_add_i32 s62, s45, 0xa000
	global_load_lds_dwordx4 v[4:5], off
	v_lshl_add_u64 v[0:1], v[0:1], 0, s[16:17]
	s_mov_b32 m0, s61
	s_add_u32 s20, s40, 0x40080
	global_load_lds_dwordx4 v[0:1], off
	v_lshl_add_u64 v[0:1], v[2:3], 0, s[16:17]
	s_mov_b32 m0, s62
	s_addc_u32 s21, s41, 0
	global_load_lds_dwordx4 v[0:1], off
	s_add_i32 m0, s45, 0x1c000
	v_lshl_add_u64 v[0:1], s[20:21], 0, v[178:179]
	global_load_lds_dwordx4 v[0:1], off
	v_lshl_add_u64 v[0:1], s[20:21], 0, v[182:183]
	s_add_i32 m0, s45, 0x1e000
	v_lshlrev_b32_e32 v2, 11, v197
	global_load_lds_dwordx4 v[0:1], off
	v_lshlrev_b32_e32 v1, 2, v189
	v_lshl_or_b32 v0, v189, 6, v190
	v_and_b32_e32 v1, 32, v1
	v_bitop3_b32 v0, v0, s5, v1 bitop3:0xde
	v_lshlrev_b32_e32 v1, 8, v192
	v_and_b32_e32 v1, 0x38000, v1
	v_or3_b32 v1, v186, v1, v2
	v_add_u32_e32 v128, v1, v187
	v_lshlrev_b32_e32 v1, 4, v198
	s_waitcnt vmcnt(6)
	s_cmpk_lt_u32 s18, 0x100
	v_and_b32_e32 v1, 0x78000, v1
	v_lshl_or_b32 v248, s19, 6, v189
	v_lshl_add_u32 v249, v188, 1, v189
	v_lshrrev_b32_e32 v250, 2, v249
	v_and_b32_e32 v251, 3, v249
	v_lshl_or_b32 v140, s19, 6, v250
	v_lshl_add_u32 v249, v251, 4, v250
	v_lshlrev_b32_e32 v249, 2, v249
	v_lshl_or_b32 v141, s9, 7, v191
	s_cselect_b64 s[18:19], -1, 0
	v_or3_b32 v1, v186, v1, v2
	s_add_i32 s63, 0, 0x10000
	s_add_i32 s64, 0, 0x14000
	v_lshl_or_b32 v142, v251, 3, s9
	v_mov_b32_e32 v129, v179
	v_add_u32_e32 v130, v1, v187
	v_mov_b32_e32 v131, v179
	v_add_u32_e32 v143, s63, v141
	v_add_u32_e32 v144, s64, v141
	v_add_u32_e32 v145, 0, v0
	s_movk_i32 s65, 0x2b00
	s_movk_i32 s66, 0x1580
	v_mov_b32_e32 v146, 0x358637bd
	s_mov_b32 s67, 0x800000
	s_add_i32 s68, s45, 0xc000
	s_barrier
	s_branch .LBB0_736

; template <class Epi, class Sched, bool ALIGN_EPI = false, bool SP2 = false>
; __device__ __forceinline__ void gemm_phase(PG8_LAS unsigned char* lds, const Gemm g, const Sched& S, const Epi& E) {
;     ...
; #pragma unroll
;     for (int a = 0; a < 2; ++a)
; #pragma unroll
;         for (int b = 0; b < 2; ++b)
; #pragma unroll
;             for (int m = 0; m < 4; ++m)
; #pragma unroll
;                 for (int n = 0; n < 2; ++n) acc[a][b][m][n] = (f32x4){0.f, 0.f, 0.f, 0.f};
.LBB0_738:
	s_ashr_i32 s21, s20, 31
	s_lshl_b64 s[24:25], s[20:21], 19
	s_add_u32 s24, s46, s24
	s_addc_u32 s25, s47, s25
	s_and_b64 s[36:37], s[26:27], exec
	s_cselect_b32 s5, s25, s39
	s_cselect_b32 s9, s24, s38
	s_ashr_i32 s23, s22, 31
	s_lshl_b64 s[36:37], s[22:23], 19
	s_add_u32 s36, s49, s36
	s_addc_u32 s37, s50, s37
	s_and_b64 s[42:43], s[26:27], exec
	s_cselect_b32 s21, s37, s41
	s_cselect_b32 s23, s36, s40
	s_add_u32 s38, s38, 0x40080
	s_addc_u32 s39, s39, 0
	s_add_u32 s69, s40, 0x100
	v_mov_b32_e32 v0, 0
	s_addc_u32 s72, s41, 0
	s_mov_b32 s73, -2
	v_mov_b32_e32 v1, v0
	v_mov_b32_e32 v2, v0
	v_mov_b32_e32 v3, v0
	v_mov_b32_e32 v4, v0
	v_mov_b32_e32 v5, v0
	v_mov_b32_e32 v6, v0
	v_mov_b32_e32 v7, v0
	v_mov_b32_e32 v16, v0
	v_mov_b32_e32 v17, v0
	v_mov_b32_e32 v18, v0
	v_mov_b32_e32 v19, v0
	v_mov_b32_e32 v20, v0
	v_mov_b32_e32 v21, v0
	v_mov_b32_e32 v22, v0
	v_mov_b32_e32 v23, v0
	v_mov_b32_e32 v32, v0
	v_mov_b32_e32 v33, v0
	v_mov_b32_e32 v34, v0
	v_mov_b32_e32 v35, v0
	v_mov_b32_e32 v36, v0
	v_mov_b32_e32 v37, v0
	v_mov_b32_e32 v38, v0
	v_mov_b32_e32 v39, v0
	v_mov_b32_e32 v48, v0
	v_mov_b32_e32 v49, v0
	v_mov_b32_e32 v50, v0
	v_mov_b32_e32 v51, v0
	v_mov_b32_e32 v52, v0
	v_mov_b32_e32 v53, v0
	v_mov_b32_e32 v54, v0
	v_mov_b32_e32 v55, v0
	v_mov_b32_e32 v8, v0
	v_mov_b32_e32 v9, v0
	v_mov_b32_e32 v10, v0
	v_mov_b32_e32 v11, v0
	v_mov_b32_e32 v12, v0
	v_mov_b32_e32 v13, v0
	v_mov_b32_e32 v14, v0
	v_mov_b32_e32 v15, v0
	v_mov_b32_e32 v24, v0
	v_mov_b32_e32 v25, v0
	v_mov_b32_e32 v26, v0
	v_mov_b32_e32 v27, v0
	v_mov_b32_e32 v28, v0
	v_mov_b32_e32 v29, v0
	v_mov_b32_e32 v30, v0
	v_mov_b32_e32 v31, v0
	v_mov_b32_e32 v40, v0
	v_mov_b32_e32 v41, v0
	v_mov_b32_e32 v42, v0
	v_mov_b32_e32 v43, v0
	v_mov_b32_e32 v44, v0
	v_mov_b32_e32 v45, v0
	v_mov_b32_e32 v46, v0
	v_mov_b32_e32 v47, v0
	v_mov_b32_e32 v56, v0
	v_mov_b32_e32 v57, v0
	v_mov_b32_e32 v58, v0
	v_mov_b32_e32 v59, v0
	v_mov_b32_e32 v60, v0
	v_mov_b32_e32 v61, v0
	v_mov_b32_e32 v62, v0
	v_mov_b32_e32 v63, v0
	v_mov_b32_e32 v64, v0
	v_mov_b32_e32 v65, v0
	v_mov_b32_e32 v66, v0
	v_mov_b32_e32 v67, v0
	v_mov_b32_e32 v68, v0
	v_mov_b32_e32 v69, v0
	v_mov_b32_e32 v70, v0
	v_mov_b32_e32 v71, v0
	v_mov_b32_e32 v80, v0
	v_mov_b32_e32 v81, v0
	v_mov_b32_e32 v82, v0
	v_mov_b32_e32 v83, v0
	v_mov_b32_e32 v84, v0
	v_mov_b32_e32 v85, v0
	v_mov_b32_e32 v86, v0
	v_mov_b32_e32 v87, v0
	v_mov_b32_e32 v96, v0
	v_mov_b32_e32 v97, v0
	v_mov_b32_e32 v98, v0
	v_mov_b32_e32 v99, v0
	v_mov_b32_e32 v100, v0
	v_mov_b32_e32 v101, v0
	v_mov_b32_e32 v102, v0
	v_mov_b32_e32 v103, v0
	v_mov_b32_e32 v112, v0
	v_mov_b32_e32 v113, v0
	v_mov_b32_e32 v114, v0
	v_mov_b32_e32 v115, v0
	v_mov_b32_e32 v116, v0
	v_mov_b32_e32 v117, v0
	v_mov_b32_e32 v118, v0
	v_mov_b32_e32 v119, v0
	v_mov_b32_e32 v72, v0
	v_mov_b32_e32 v73, v0
	v_mov_b32_e32 v74, v0
	v_mov_b32_e32 v75, v0
	v_mov_b32_e32 v76, v0
	v_mov_b32_e32 v77, v0
	v_mov_b32_e32 v78, v0
	v_mov_b32_e32 v79, v0
	v_mov_b32_e32 v88, v0
	v_mov_b32_e32 v89, v0
	v_mov_b32_e32 v90, v0
	v_mov_b32_e32 v91, v0
	v_mov_b32_e32 v92, v0
	v_mov_b32_e32 v93, v0
	v_mov_b32_e32 v94, v0
	v_mov_b32_e32 v95, v0
	v_mov_b32_e32 v104, v0
	v_mov_b32_e32 v105, v0
	v_mov_b32_e32 v106, v0
	v_mov_b32_e32 v107, v0
	v_mov_b32_e32 v108, v0
	v_mov_b32_e32 v109, v0
	v_mov_b32_e32 v110, v0
	v_mov_b32_e32 v111, v0
	v_mov_b32_e32 v120, v0
	v_mov_b32_e32 v121, v0
	v_mov_b32_e32 v122, v0
	v_mov_b32_e32 v123, v0
	v_mov_b32_e32 v124, v0
	v_mov_b32_e32 v125, v0
	v_mov_b32_e32 v126, v0
	v_mov_b32_e32 v127, v0
	v_lshl_add_u32 v238, s8, 8, v248
	v_ashrrev_i32_e32 v239, 31, v238
	v_lshl_add_u64 v[238:239], v[238:239], 2, s[12:13]
	global_load_dword v240, v[238:239], off
	global_load_dword v241, v[238:239], off offset:64
	global_load_dword v242, v[238:239], off offset:128
	global_load_dword v243, v[238:239], off offset:192
	global_load_dword v244, v[238:239], off offset:512
	global_load_dword v245, v[238:239], off offset:576
	global_load_dword v246, v[238:239], off offset:640
	global_load_dword v247, v[238:239], off offset:704

;     DI void operator()(const f32x4 (&acc)[2][2][4][2], const Unit& u, int wr, int wc, int fr, int fq) const {
; #pragma unroll
;         for (int ai = 0; ai < 2; ++ai)
; #pragma unroll
;             for (int m = 0; m < 4; ++m) {
;                 const int r = u.pm * BM + ai * HALF + wr * 64 + m * 16 + fr;
; #pragma unroll
;                 for (int bj = 0; bj < 2; ++bj) f(r, u.pn * BM + bj * HALF + wc * 32 + 8 * fq, acc[ai][bj][m][0], acc[ai][bj][m][1]);
;                 asm volatile("" ::: "memory");
;             }
.LBB0_742:
	v_lshl_add_u32 v134, s8, 8, v140
	v_lshl_or_b32 v132, s4, 8, v142
	v_ashrrev_i32_e32 v135, 31, v134
	v_mad_i64_i32 v[136:137], s[4:5], v134, s65, 0
	v_cmp_gt_i32_e32 vcc, s66, v132
	v_lshl_add_u64 v[136:137], s[10:11], 0, v[136:137]
	v_ashrrev_i32_e32 v133, 31, v132
	v_lshl_add_u64 v[138:139], v[134:135], 2, s[12:13]
	s_and_saveexec_b64 s[8:9], vcc
	s_cbranch_execz .LBB0_744
	v_mov_b32_e32 v135, v240
	v_lshl_add_u64 v[148:149], v[132:133], 1, v[136:137]
	v_fmamk_f32 v135, v135, 0x3a800000, v146
	v_mul_f32_e32 v147, 0x4b800000, v135
	v_cmp_gt_f32_e64 s[4:5], s67, v135
	s_nop 1
	v_cndmask_b32_e64 v135, v135, v147, s[4:5]
	v_rsq_f32_e32 v135, v135
	s_nop 0
	v_mul_f32_e32 v147, 0x45800000, v135
	v_cndmask_b32_e64 v150, v135, v147, s[4:5]
	v_pk_mul_f32 v[126:127], v[126:127], v[150:151] op_sel_hi:[1,0]
	v_pk_mul_f32 v[124:125], v[124:125], v[150:151] op_sel_hi:[1,0]
	v_pk_mul_f32 v[152:153], v[122:123], v[150:151] op_sel_hi:[1,0]
	v_pk_mul_f32 v[122:123], v[120:121], v[150:151] op_sel_hi:[1,0]
	v_cvt_pk_bf16_f32 v120, v124, v125
	v_cvt_pk_bf16_f32 v121, v126, v127
	v_cvt_pk_bf16_f32 v122, v122, v123
	v_cvt_pk_bf16_f32 v123, v152, v153
	ds_bpermute_b32 v120, v249, v120
	ds_bpermute_b32 v121, v249, v121
	ds_bpermute_b32 v122, v249, v122
	ds_bpermute_b32 v123, v249, v123
	s_waitcnt lgkmcnt(0)
	global_store_dwordx4 v[148:149], v[120:123], off
.LBB0_744:
	s_or_b64 exec, exec, s[8:9]
	s_nop 0
	v_or_b32_e32 v120, 0x80, v132
	v_cmp_gt_i32_e64 s[4:5], s66, v120
	s_and_saveexec_b64 s[38:39], s[4:5]
	s_cbranch_execz .LBB0_746
	v_mov_b32_e32 v120, v240
	v_fmamk_f32 v120, v120, 0x3a800000, v146
	v_mul_f32_e32 v121, 0x4b800000, v120
	v_cmp_gt_f32_e64 s[8:9], s67, v120
	s_nop 1
	v_cndmask_b32_e64 v120, v120, v121, s[8:9]
	v_rsq_f32_e32 v122, v120
	v_lshl_add_u64 v[120:121], v[132:133], 1, v[136:137]
	v_mul_f32_e32 v123, 0x45800000, v122
	v_cndmask_b32_e64 v122, v122, v123, s[8:9]
	v_pk_mul_f32 v[118:119], v[118:119], v[122:123] op_sel_hi:[1,0]
	v_pk_mul_f32 v[116:117], v[116:117], v[122:123] op_sel_hi:[1,0]
	v_pk_mul_f32 v[124:125], v[114:115], v[122:123] op_sel_hi:[1,0]
	v_pk_mul_f32 v[114:115], v[112:113], v[122:123] op_sel_hi:[1,0]
	v_cvt_pk_bf16_f32 v112, v116, v117
	v_cvt_pk_bf16_f32 v113, v118, v119
	v_cvt_pk_bf16_f32 v114, v114, v115
	v_cvt_pk_bf16_f32 v115, v124, v125
	ds_bpermute_b32 v112, v249, v112
	ds_bpermute_b32 v113, v249, v113
	ds_bpermute_b32 v114, v249, v114
	ds_bpermute_b32 v115, v249, v115
	s_waitcnt lgkmcnt(0)
	global_store_dwordx4 v[120:121], v[112:115], off offset:256
.LBB0_746:
	s_or_b64 exec, exec, s[38:39]
	s_nop 0
	v_or_b32_e32 v114, 16, v134
	v_ashrrev_i32_e32 v115, 31, v114
	v_mad_i64_i32 v[112:113], s[8:9], v114, s65, 0
	v_lshl_add_u64 v[112:113], s[10:11], 0, v[112:113]
	v_lshl_add_u64 v[114:115], v[114:115], 2, s[12:13]
	s_and_saveexec_b64 s[38:39], vcc
	s_cbranch_execz .LBB0_748
	v_mov_b32_e32 v116, v241
	v_fmamk_f32 v116, v116, 0x3a800000, v146
	v_mul_f32_e32 v117, 0x4b800000, v116
	v_cmp_gt_f32_e64 s[8:9], s67, v116
	s_nop 1
	v_cndmask_b32_e64 v116, v116, v117, s[8:9]
	v_rsq_f32_e32 v118, v116
	v_lshl_add_u64 v[116:117], v[132:133], 1, v[112:113]
	v_mul_f32_e32 v119, 0x45800000, v118
	v_cndmask_b32_e64 v118, v118, v119, s[8:9]
	v_pk_mul_f32 v[110:111], v[110:111], v[118:119] op_sel_hi:[1,0]
	v_pk_mul_f32 v[108:109], v[108:109], v[118:119] op_sel_hi:[1,0]
	v_pk_mul_f32 v[120:121], v[106:107], v[118:119] op_sel_hi:[1,0]
	v_pk_mul_f32 v[106:107], v[104:105], v[118:119] op_sel_hi:[1,0]
	v_cvt_pk_bf16_f32 v104, v108, v109
	v_cvt_pk_bf16_f32 v105, v110, v111
	v_cvt_pk_bf16_f32 v106, v106, v107
	v_cvt_pk_bf16_f32 v107, v120, v121
	ds_bpermute_b32 v104, v249, v104
	ds_bpermute_b32 v105, v249, v105
	ds_bpermute_b32 v106, v249, v106
	ds_bpermute_b32 v107, v249, v107
	s_waitcnt lgkmcnt(0)
	global_store_dwordx4 v[116:117], v[104:107], off
.LBB0_748:
	s_or_b64 exec, exec, s[38:39]
	s_and_saveexec_b64 s[38:39], s[4:5]
	s_cbranch_execz .LBB0_750
	v_mov_b32_e32 v104, v241
	v_fmamk_f32 v104, v104, 0x3a800000, v146
	v_mul_f32_e32 v105, 0x4b800000, v104
	v_cmp_gt_f32_e64 s[8:9], s67, v104
	s_nop 1
	v_cndmask_b32_e64 v104, v104, v105, s[8:9]
	v_rsq_f32_e32 v106, v104
	v_lshl_add_u64 v[104:105], v[132:133], 1, v[112:113]
	v_mul_f32_e32 v107, 0x45800000, v106
	v_cndmask_b32_e64 v106, v106, v107, s[8:9]
	v_pk_mul_f32 v[102:103], v[102:103], v[106:107] op_sel_hi:[1,0]
	v_pk_mul_f32 v[100:101], v[100:101], v[106:107] op_sel_hi:[1,0]
	v_pk_mul_f32 v[108:109], v[98:99], v[106:107] op_sel_hi:[1,0]
	v_pk_mul_f32 v[98:99], v[96:97], v[106:107] op_sel_hi:[1,0]
	v_cvt_pk_bf16_f32 v96, v100, v101
	v_cvt_pk_bf16_f32 v97, v102, v103
	v_cvt_pk_bf16_f32 v98, v98, v99
	v_cvt_pk_bf16_f32 v99, v108, v109
	ds_bpermute_b32 v96, v249, v96
	ds_bpermute_b32 v97, v249, v97
	ds_bpermute_b32 v98, v249, v98
	ds_bpermute_b32 v99, v249, v99
	s_waitcnt lgkmcnt(0)
	global_store_dwordx4 v[104:105], v[96:99], off offset:256
.LBB0_750:
	s_or_b64 exec, exec, s[38:39]
	s_nop 0
	v_or_b32_e32 v98, 32, v134
	v_ashrrev_i32_e32 v99, 31, v98
	v_mad_i64_i32 v[96:97], s[8:9], v98, s65, 0
	v_lshl_add_u64 v[96:97], s[10:11], 0, v[96:97]
	v_lshl_add_u64 v[98:99], v[98:99], 2, s[12:13]
	s_and_saveexec_b64 s[38:39], vcc
	s_cbranch_execz .LBB0_752
	v_mov_b32_e32 v100, v242
	v_fmamk_f32 v100, v100, 0x3a800000, v146
	v_mul_f32_e32 v101, 0x4b800000, v100
	v_cmp_gt_f32_e64 s[8:9], s67, v100
	s_nop 1
	v_cndmask_b32_e64 v100, v100, v101, s[8:9]
	v_rsq_f32_e32 v102, v100
	v_lshl_add_u64 v[100:101], v[132:133], 1, v[96:97]
	v_mul_f32_e32 v103, 0x45800000, v102
	v_cndmask_b32_e64 v102, v102, v103, s[8:9]
	v_pk_mul_f32 v[94:95], v[94:95], v[102:103] op_sel_hi:[1,0]
	v_pk_mul_f32 v[92:93], v[92:93], v[102:103] op_sel_hi:[1,0]
	v_pk_mul_f32 v[104:105], v[90:91], v[102:103] op_sel_hi:[1,0]
	v_pk_mul_f32 v[90:91], v[88:89], v[102:103] op_sel_hi:[1,0]
	v_cvt_pk_bf16_f32 v88, v92, v93
	v_cvt_pk_bf16_f32 v89, v94, v95
	v_cvt_pk_bf16_f32 v90, v90, v91
	v_cvt_pk_bf16_f32 v91, v104, v105
	ds_bpermute_b32 v88, v249, v88
	ds_bpermute_b32 v89, v249, v89
	ds_bpermute_b32 v90, v249, v90
	ds_bpermute_b32 v91, v249, v91
	s_waitcnt lgkmcnt(0)
	global_store_dwordx4 v[100:101], v[88:91], off
;     DI void operator()(const f32x4 (&acc)[2][2][4][2], const Unit& u, int wr, int wc, int fr, int fq) const {
; #pragma unroll
;         for (int ai = 0; ai < 2; ++ai)
; #pragma unroll
;             for (int m = 0; m < 4; ++m) {
;                 const int r = u.pm * BM + ai * HALF + wr * 64 + m * 16 + fr;
; #pragma unroll
;                 for (int bj = 0; bj < 2; ++bj) f(r, u.pn * BM + bj * HALF + wc * 32 + 8 * fq, acc[ai][bj][m][0], acc[ai][bj][m][1]);
;                 asm volatile("" ::: "memory");
;             }
.LBB0_752:
	s_or_b64 exec, exec, s[38:39]
	s_and_saveexec_b64 s[38:39], s[4:5]
	s_cbranch_execz .LBB0_754
	v_mov_b32_e32 v88, v242
	v_fmamk_f32 v88, v88, 0x3a800000, v146
	v_mul_f32_e32 v89, 0x4b800000, v88
	v_cmp_gt_f32_e64 s[8:9], s67, v88
	s_nop 1
	v_cndmask_b32_e64 v88, v88, v89, s[8:9]
	v_rsq_f32_e32 v90, v88
	v_lshl_add_u64 v[88:89], v[132:133], 1, v[96:97]
	v_mul_f32_e32 v91, 0x45800000, v90
	v_cndmask_b32_e64 v90, v90, v91, s[8:9]
	v_pk_mul_f32 v[86:87], v[86:87], v[90:91] op_sel_hi:[1,0]
	v_pk_mul_f32 v[84:85], v[84:85], v[90:91] op_sel_hi:[1,0]
	v_pk_mul_f32 v[92:93], v[82:83], v[90:91] op_sel_hi:[1,0]
	v_pk_mul_f32 v[82:83], v[80:81], v[90:91] op_sel_hi:[1,0]
	v_cvt_pk_bf16_f32 v80, v84, v85
	v_cvt_pk_bf16_f32 v81, v86, v87
	v_cvt_pk_bf16_f32 v82, v82, v83
	v_cvt_pk_bf16_f32 v83, v92, v93
	ds_bpermute_b32 v80, v249, v80
	ds_bpermute_b32 v81, v249, v81
	ds_bpermute_b32 v82, v249, v82
	ds_bpermute_b32 v83, v249, v83
	s_waitcnt lgkmcnt(0)
	global_store_dwordx4 v[88:89], v[80:83], off offset:256
.LBB0_754:
	s_or_b64 exec, exec, s[38:39]
	s_nop 0
	v_or_b32_e32 v82, 48, v134
	v_ashrrev_i32_e32 v83, 31, v82
	v_mad_i64_i32 v[80:81], s[8:9], v82, s65, 0
	v_lshl_add_u64 v[80:81], s[10:11], 0, v[80:81]
	v_lshl_add_u64 v[82:83], v[82:83], 2, s[12:13]
	s_and_saveexec_b64 s[38:39], vcc
	s_cbranch_execz .LBB0_756
	v_mov_b32_e32 v84, v243
	v_fmamk_f32 v84, v84, 0x3a800000, v146
	v_mul_f32_e32 v85, 0x4b800000, v84
	v_cmp_gt_f32_e64 s[8:9], s67, v84
	s_nop 1
	v_cndmask_b32_e64 v84, v84, v85, s[8:9]
	v_rsq_f32_e32 v86, v84
	v_lshl_add_u64 v[84:85], v[132:133], 1, v[80:81]
	v_mul_f32_e32 v87, 0x45800000, v86
	v_cndmask_b32_e64 v86, v86, v87, s[8:9]
	v_pk_mul_f32 v[78:79], v[78:79], v[86:87] op_sel_hi:[1,0]
	v_pk_mul_f32 v[76:77], v[76:77], v[86:87] op_sel_hi:[1,0]
	v_pk_mul_f32 v[88:89], v[74:75], v[86:87] op_sel_hi:[1,0]
	v_pk_mul_f32 v[74:75], v[72:73], v[86:87] op_sel_hi:[1,0]
	v_cvt_pk_bf16_f32 v72, v76, v77
	v_cvt_pk_bf16_f32 v73, v78, v79
	v_cvt_pk_bf16_f32 v74, v74, v75
	v_cvt_pk_bf16_f32 v75, v88, v89
	ds_bpermute_b32 v72, v249, v72
	ds_bpermute_b32 v73, v249, v73
	ds_bpermute_b32 v74, v249, v74
	ds_bpermute_b32 v75, v249, v75
	s_waitcnt lgkmcnt(0)
	global_store_dwordx4 v[84:85], v[72:75], off
.LBB0_756:
	s_or_b64 exec, exec, s[38:39]
	s_and_saveexec_b64 s[38:39], s[4:5]
	s_cbranch_execz .LBB0_758
	v_mov_b32_e32 v72, v243
	v_fmamk_f32 v72, v72, 0x3a800000, v146
	v_mul_f32_e32 v73, 0x4b800000, v72
	v_cmp_gt_f32_e64 s[8:9], s67, v72
	s_nop 1
	v_cndmask_b32_e64 v72, v72, v73, s[8:9]
	v_rsq_f32_e32 v74, v72
	v_lshl_add_u64 v[72:73], v[132:133], 1, v[80:81]
	v_mul_f32_e32 v75, 0x45800000, v74
	v_cndmask_b32_e64 v74, v74, v75, s[8:9]
	v_pk_mul_f32 v[70:71], v[70:71], v[74:75] op_sel_hi:[1,0]
	v_pk_mul_f32 v[68:69], v[68:69], v[74:75] op_sel_hi:[1,0]
	v_pk_mul_f32 v[76:77], v[66:67], v[74:75] op_sel_hi:[1,0]
	v_pk_mul_f32 v[66:67], v[64:65], v[74:75] op_sel_hi:[1,0]
	v_cvt_pk_bf16_f32 v64, v68, v69
	v_cvt_pk_bf16_f32 v65, v70, v71
	v_cvt_pk_bf16_f32 v66, v66, v67
	v_cvt_pk_bf16_f32 v67, v76, v77
	ds_bpermute_b32 v64, v249, v64
	ds_bpermute_b32 v65, v249, v65
	ds_bpermute_b32 v66, v249, v66
	ds_bpermute_b32 v67, v249, v67
	s_waitcnt lgkmcnt(0)
	global_store_dwordx4 v[72:73], v[64:67], off offset:256
.LBB0_758:
	s_or_b64 exec, exec, s[38:39]
	s_nop 0
	v_add_u32_e32 v66, 0x80, v134
	v_ashrrev_i32_e32 v67, 31, v66
	v_mad_i64_i32 v[64:65], s[8:9], v66, s65, 0
	v_lshl_add_u64 v[64:65], s[10:11], 0, v[64:65]
	v_lshl_add_u64 v[66:67], v[66:67], 2, s[12:13]
	s_and_saveexec_b64 s[38:39], vcc
	s_cbranch_execz .LBB0_760
	v_mov_b32_e32 v68, v244
	v_fmamk_f32 v68, v68, 0x3a800000, v146
	v_mul_f32_e32 v69, 0x4b800000, v68
	v_cmp_gt_f32_e64 s[8:9], s67, v68
	s_nop 1
	v_cndmask_b32_e64 v68, v68, v69, s[8:9]
	v_rsq_f32_e32 v70, v68
	v_lshl_add_u64 v[68:69], v[132:133], 1, v[64:65]
	v_mul_f32_e32 v71, 0x45800000, v70
	v_cndmask_b32_e64 v70, v70, v71, s[8:9]
	v_pk_mul_f32 v[62:63], v[62:63], v[70:71] op_sel_hi:[1,0]
	v_pk_mul_f32 v[60:61], v[60:61], v[70:71] op_sel_hi:[1,0]
	v_pk_mul_f32 v[72:73], v[58:59], v[70:71] op_sel_hi:[1,0]
	v_pk_mul_f32 v[58:59], v[56:57], v[70:71] op_sel_hi:[1,0]
	v_cvt_pk_bf16_f32 v56, v60, v61
	v_cvt_pk_bf16_f32 v57, v62, v63
	v_cvt_pk_bf16_f32 v58, v58, v59
	v_cvt_pk_bf16_f32 v59, v72, v73
	ds_bpermute_b32 v56, v249, v56
	ds_bpermute_b32 v57, v249, v57
	ds_bpermute_b32 v58, v249, v58
	ds_bpermute_b32 v59, v249, v59
	s_waitcnt lgkmcnt(0)
	global_store_dwordx4 v[68:69], v[56:59], off
.LBB0_760:
	s_or_b64 exec, exec, s[38:39]
	s_and_saveexec_b64 s[38:39], s[4:5]
	s_cbranch_execz .LBB0_762
	v_mov_b32_e32 v56, v244
	v_fmamk_f32 v56, v56, 0x3a800000, v146
	v_mul_f32_e32 v57, 0x4b800000, v56
	v_cmp_gt_f32_e64 s[8:9], s67, v56
	s_nop 1
	v_cndmask_b32_e64 v56, v56, v57, s[8:9]
	v_rsq_f32_e32 v58, v56
	v_lshl_add_u64 v[56:57], v[132:133], 1, v[64:65]
	v_mul_f32_e32 v59, 0x45800000, v58
	v_cndmask_b32_e64 v58, v58, v59, s[8:9]
	v_pk_mul_f32 v[54:55], v[54:55], v[58:59] op_sel_hi:[1,0]
	v_pk_mul_f32 v[52:53], v[52:53], v[58:59] op_sel_hi:[1,0]
	v_pk_mul_f32 v[60:61], v[50:51], v[58:59] op_sel_hi:[1,0]
	v_pk_mul_f32 v[50:51], v[48:49], v[58:59] op_sel_hi:[1,0]
	v_cvt_pk_bf16_f32 v48, v52, v53
	v_cvt_pk_bf16_f32 v49, v54, v55
	v_cvt_pk_bf16_f32 v50, v50, v51
	v_cvt_pk_bf16_f32 v51, v60, v61
	ds_bpermute_b32 v48, v249, v48
	ds_bpermute_b32 v49, v249, v49
	ds_bpermute_b32 v50, v249, v50
	ds_bpermute_b32 v51, v249, v51
	s_waitcnt lgkmcnt(0)
	global_store_dwordx4 v[56:57], v[48:51], off offset:256
;     DI void operator()(const f32x4 (&acc)[2][2][4][2], const Unit& u, int wr, int wc, int fr, int fq) const {
; #pragma unroll
;         for (int ai = 0; ai < 2; ++ai)
; #pragma unroll
;             for (int m = 0; m < 4; ++m) {
;                 const int r = u.pm * BM + ai * HALF + wr * 64 + m * 16 + fr;
; #pragma unroll
;                 for (int bj = 0; bj < 2; ++bj) f(r, u.pn * BM + bj * HALF + wc * 32 + 8 * fq, acc[ai][bj][m][0], acc[ai][bj][m][1]);
;                 asm volatile("" ::: "memory");
;             }
.LBB0_762:
	s_or_b64 exec, exec, s[38:39]
	s_nop 0
	v_add_u32_e32 v50, 0x90, v134
	v_ashrrev_i32_e32 v51, 31, v50
	v_mad_i64_i32 v[48:49], s[8:9], v50, s65, 0
	v_lshl_add_u64 v[48:49], s[10:11], 0, v[48:49]
	v_lshl_add_u64 v[50:51], v[50:51], 2, s[12:13]
	s_and_saveexec_b64 s[38:39], vcc
	s_cbranch_execz .LBB0_764
	v_mov_b32_e32 v52, v245
	v_fmamk_f32 v52, v52, 0x3a800000, v146
	v_mul_f32_e32 v53, 0x4b800000, v52
	v_cmp_gt_f32_e64 s[8:9], s67, v52
	s_nop 1
	v_cndmask_b32_e64 v52, v52, v53, s[8:9]
	v_rsq_f32_e32 v54, v52
	v_lshl_add_u64 v[52:53], v[132:133], 1, v[48:49]
	v_mul_f32_e32 v55, 0x45800000, v54
	v_cndmask_b32_e64 v54, v54, v55, s[8:9]
	v_pk_mul_f32 v[46:47], v[46:47], v[54:55] op_sel_hi:[1,0]
	v_pk_mul_f32 v[44:45], v[44:45], v[54:55] op_sel_hi:[1,0]
	v_pk_mul_f32 v[56:57], v[42:43], v[54:55] op_sel_hi:[1,0]
	v_pk_mul_f32 v[42:43], v[40:41], v[54:55] op_sel_hi:[1,0]
	v_cvt_pk_bf16_f32 v40, v44, v45
	v_cvt_pk_bf16_f32 v41, v46, v47
	v_cvt_pk_bf16_f32 v42, v42, v43
	v_cvt_pk_bf16_f32 v43, v56, v57
	ds_bpermute_b32 v40, v249, v40
	ds_bpermute_b32 v41, v249, v41
	ds_bpermute_b32 v42, v249, v42
	ds_bpermute_b32 v43, v249, v43
	s_waitcnt lgkmcnt(0)
	global_store_dwordx4 v[52:53], v[40:43], off
.LBB0_764:
	s_or_b64 exec, exec, s[38:39]
	s_and_saveexec_b64 s[38:39], s[4:5]
	s_cbranch_execz .LBB0_766
	v_mov_b32_e32 v40, v245
	v_fmamk_f32 v40, v40, 0x3a800000, v146
	v_mul_f32_e32 v41, 0x4b800000, v40
	v_cmp_gt_f32_e64 s[8:9], s67, v40
	s_nop 1
	v_cndmask_b32_e64 v40, v40, v41, s[8:9]
	v_rsq_f32_e32 v42, v40
	v_lshl_add_u64 v[40:41], v[132:133], 1, v[48:49]
	v_mul_f32_e32 v43, 0x45800000, v42
	v_cndmask_b32_e64 v42, v42, v43, s[8:9]
	v_pk_mul_f32 v[38:39], v[38:39], v[42:43] op_sel_hi:[1,0]
	v_pk_mul_f32 v[36:37], v[36:37], v[42:43] op_sel_hi:[1,0]
	v_pk_mul_f32 v[44:45], v[34:35], v[42:43] op_sel_hi:[1,0]
	v_pk_mul_f32 v[34:35], v[32:33], v[42:43] op_sel_hi:[1,0]
	v_cvt_pk_bf16_f32 v32, v36, v37
	v_cvt_pk_bf16_f32 v33, v38, v39
	v_cvt_pk_bf16_f32 v34, v34, v35
	v_cvt_pk_bf16_f32 v35, v44, v45
	ds_bpermute_b32 v32, v249, v32
	ds_bpermute_b32 v33, v249, v33
	ds_bpermute_b32 v34, v249, v34
	ds_bpermute_b32 v35, v249, v35
	s_waitcnt lgkmcnt(0)
	global_store_dwordx4 v[40:41], v[32:35], off offset:256
.LBB0_766:
	s_or_b64 exec, exec, s[38:39]
	s_nop 0
	v_add_u32_e32 v34, 0xa0, v134
	v_ashrrev_i32_e32 v35, 31, v34
	v_mad_i64_i32 v[32:33], s[8:9], v34, s65, 0
	v_lshl_add_u64 v[32:33], s[10:11], 0, v[32:33]
	v_lshl_add_u64 v[34:35], v[34:35], 2, s[12:13]
	s_and_saveexec_b64 s[38:39], vcc
	s_cbranch_execz .LBB0_768
	v_mov_b32_e32 v36, v246
	v_fmamk_f32 v36, v36, 0x3a800000, v146
	v_mul_f32_e32 v37, 0x4b800000, v36
	v_cmp_gt_f32_e64 s[8:9], s67, v36
	s_nop 1
	v_cndmask_b32_e64 v36, v36, v37, s[8:9]
	v_rsq_f32_e32 v38, v36
	v_lshl_add_u64 v[36:37], v[132:133], 1, v[32:33]
	v_mul_f32_e32 v39, 0x45800000, v38
	v_cndmask_b32_e64 v38, v38, v39, s[8:9]
	v_pk_mul_f32 v[30:31], v[30:31], v[38:39] op_sel_hi:[1,0]
	v_pk_mul_f32 v[28:29], v[28:29], v[38:39] op_sel_hi:[1,0]
	v_pk_mul_f32 v[40:41], v[26:27], v[38:39] op_sel_hi:[1,0]
	v_pk_mul_f32 v[26:27], v[24:25], v[38:39] op_sel_hi:[1,0]
	v_cvt_pk_bf16_f32 v24, v28, v29
	v_cvt_pk_bf16_f32 v25, v30, v31
	v_cvt_pk_bf16_f32 v26, v26, v27
	v_cvt_pk_bf16_f32 v27, v40, v41
	ds_bpermute_b32 v24, v249, v24
	ds_bpermute_b32 v25, v249, v25
	ds_bpermute_b32 v26, v249, v26
	ds_bpermute_b32 v27, v249, v27
	s_waitcnt lgkmcnt(0)
	global_store_dwordx4 v[36:37], v[24:27], off
.LBB0_768:
	s_or_b64 exec, exec, s[38:39]
	s_and_saveexec_b64 s[38:39], s[4:5]
	s_cbranch_execz .LBB0_770
	v_mov_b32_e32 v24, v246
	v_fmamk_f32 v24, v24, 0x3a800000, v146
	v_mul_f32_e32 v25, 0x4b800000, v24
	v_cmp_gt_f32_e64 s[8:9], s67, v24
	s_nop 1
	v_cndmask_b32_e64 v24, v24, v25, s[8:9]
	v_rsq_f32_e32 v26, v24
	v_lshl_add_u64 v[24:25], v[132:133], 1, v[32:33]
	v_mul_f32_e32 v27, 0x45800000, v26
	v_cndmask_b32_e64 v26, v26, v27, s[8:9]
	v_pk_mul_f32 v[22:23], v[22:23], v[26:27] op_sel_hi:[1,0]
	v_pk_mul_f32 v[20:21], v[20:21], v[26:27] op_sel_hi:[1,0]
	v_pk_mul_f32 v[28:29], v[18:19], v[26:27] op_sel_hi:[1,0]
	v_pk_mul_f32 v[18:19], v[16:17], v[26:27] op_sel_hi:[1,0]
	v_cvt_pk_bf16_f32 v16, v20, v21
	v_cvt_pk_bf16_f32 v17, v22, v23
	v_cvt_pk_bf16_f32 v18, v18, v19
	v_cvt_pk_bf16_f32 v19, v28, v29
	ds_bpermute_b32 v16, v249, v16
	ds_bpermute_b32 v17, v249, v17
	ds_bpermute_b32 v18, v249, v18
	ds_bpermute_b32 v19, v249, v19
	s_waitcnt lgkmcnt(0)
	global_store_dwordx4 v[24:25], v[16:19], off offset:256
.LBB0_770:
	s_or_b64 exec, exec, s[38:39]
	s_nop 0
	v_add_u32_e32 v18, 0xb0, v134
	v_ashrrev_i32_e32 v19, 31, v18
	v_mad_i64_i32 v[16:17], s[8:9], v18, s65, 0
	v_lshl_add_u64 v[16:17], s[10:11], 0, v[16:17]
	v_lshl_add_u64 v[18:19], v[18:19], 2, s[12:13]
	s_and_saveexec_b64 s[8:9], vcc
	s_cbranch_execz .LBB0_772
	v_mov_b32_e32 v20, v247
	v_fmamk_f32 v20, v20, 0x3a800000, v146
	v_mul_f32_e32 v21, 0x4b800000, v20
	v_cmp_gt_f32_e32 vcc, s67, v20
	s_nop 1
	v_cndmask_b32_e32 v20, v20, v21, vcc
	v_rsq_f32_e32 v22, v20
	v_lshl_add_u64 v[20:21], v[132:133], 1, v[16:17]
	v_mul_f32_e32 v23, 0x45800000, v22
	v_cndmask_b32_e32 v22, v22, v23, vcc
	v_pk_mul_f32 v[14:15], v[14:15], v[22:23] op_sel_hi:[1,0]
	v_pk_mul_f32 v[12:13], v[12:13], v[22:23] op_sel_hi:[1,0]
	v_pk_mul_f32 v[24:25], v[10:11], v[22:23] op_sel_hi:[1,0]
	v_pk_mul_f32 v[10:11], v[8:9], v[22:23] op_sel_hi:[1,0]
	v_cvt_pk_bf16_f32 v8, v12, v13
	v_cvt_pk_bf16_f32 v9, v14, v15
	v_cvt_pk_bf16_f32 v10, v10, v11
	v_cvt_pk_bf16_f32 v11, v24, v25
	ds_bpermute_b32 v8, v249, v8
	ds_bpermute_b32 v9, v249, v9
	ds_bpermute_b32 v10, v249, v10
	ds_bpermute_b32 v11, v249, v11
	s_waitcnt lgkmcnt(0)
	global_store_dwordx4 v[20:21], v[8:11], off
.LBB0_772:
	s_or_b64 exec, exec, s[8:9]
	s_and_saveexec_b64 s[8:9], s[4:5]
	s_cbranch_execz .LBB0_774
	v_mov_b32_e32 v8, v247
	v_fmamk_f32 v8, v8, 0x3a800000, v146
	v_mul_f32_e32 v9, 0x4b800000, v8
	v_cmp_gt_f32_e32 vcc, s67, v8
	s_nop 1
	v_cndmask_b32_e32 v8, v8, v9, vcc
	v_rsq_f32_e32 v10, v8
	v_lshl_add_u64 v[8:9], v[132:133], 1, v[16:17]
	v_mul_f32_e32 v11, 0x45800000, v10
	v_cndmask_b32_e32 v10, v10, v11, vcc
	v_pk_mul_f32 v[6:7], v[6:7], v[10:11] op_sel_hi:[1,0]
	v_pk_mul_f32 v[4:5], v[4:5], v[10:11] op_sel_hi:[1,0]
	v_pk_mul_f32 v[12:13], v[2:3], v[10:11] op_sel_hi:[1,0]
	v_pk_mul_f32 v[2:3], v[0:1], v[10:11] op_sel_hi:[1,0]
	v_cvt_pk_bf16_f32 v0, v4, v5
	v_cvt_pk_bf16_f32 v1, v6, v7
	v_cvt_pk_bf16_f32 v2, v2, v3
	v_cvt_pk_bf16_f32 v3, v12, v13
	ds_bpermute_b32 v0, v249, v0
	ds_bpermute_b32 v1, v249, v1
	ds_bpermute_b32 v2, v249, v2
	ds_bpermute_b32 v3, v249, v3
	s_waitcnt lgkmcnt(0)
	global_store_dwordx4 v[8:9], v[0:3], off offset:256

; #define PG8_STAGE(bufoff, gbase, voff) do { _Pragma("unroll") for (int _i = 0; _i < 2; ++_i) \
;         __builtin_amdgcn_global_load_lds((const unsigned*)((const char*)(gbase) + (voff)[_i]), (PG8_LAS unsigned*)(lds + (bufoff) + ldsw + _i * 8192), 16, 0, 0); } while (0)
; #define PG8_WAIT_V(n) asm volatile("s_waitcnt vmcnt(" #n ")" ::: "memory")
; #define PG8_BAR __builtin_amdgcn_s_barrier()
; template <class Epi, class Sched, bool ALIGN_EPI = false, bool SP2 = false>
; __device__ __forceinline__ void gemm_phase(PG8_LAS unsigned char* lds, const Gemm g, const Sched& S, const Epi& E) {
;     ...
;         PG8_STAGE(PG8_SB(0, 0), cB, voffB); PG8_STAGE(PG8_SB(0, 1), cB + hstep, voffB); PG8_STAGE(PG8_SA(0, 0), cA, voffA); PG8_STAGE(PG8_SA(0, 1), cA + hstep, voffA);
;         if (wr == 1) PG8_BAR;
;         PG8_WAIT_V(2); PG8_BAR;
;         PG8_STAGE(PG8_SB(1, 0), cB + kstep, voffB); PG8_STAGE(PG8_SA(1, 0), cA + kstep, voffA); PG8_STAGE(PG8_SB(1, 1), cB + hstep + kstep, voffB);
;         PG8_WAIT_V(6); PG8_BAR;
;     DI void operator()(const f32x4 (&acc)[2][2][4][2], const Unit& u, int wr, int wc, int fr, int fq) const {
;     ...
;                 const int r = u.pm * BM + ai * HALF + wr * 64 + m * 16 + fr;
; #pragma unroll
;                 for (int bj = 0; bj < 2; ++bj) f(r, u.pn * BM + bj * HALF + wc * 32 + 8 * fq, acc[ai][bj][m][0], acc[ai][bj][m][1]);
.LBB0_837:
	s_add_u32 s16, s28, 0x3e550000
	s_addc_u32 s17, s29, 0
	s_lshl_b32 s18, s18, 5
	s_and_b32 s24, s18, 0x60
	s_mov_b64 s[18:19], 0x80
	s_add_i32 m0, s61, 0x18000
	v_lshl_add_u64 v[6:7], v[6:7], 0, s[18:19]
	s_lshl_b32 s9, s21, 13
	s_waitcnt vmcnt(2)
	s_barrier
	global_load_lds_dwordx4 v[6:7], off
	v_lshl_add_u64 v[4:5], v[4:5], 0, s[18:19]
	s_add_i32 m0, s61, 0x1a000
	s_add_i32 s66, s61, 0x8000
	s_add_i32 s67, s61, 0xa000
	global_load_lds_dwordx4 v[4:5], off
	v_lshl_add_u64 v[0:1], v[0:1], 0, s[18:19]
	s_mov_b32 m0, s66
	s_add_u32 s22, s42, 0x40080
	global_load_lds_dwordx4 v[0:1], off
	v_lshl_add_u64 v[0:1], v[2:3], 0, s[18:19]
	s_mov_b32 m0, s67
	s_addc_u32 s23, s43, 0
	global_load_lds_dwordx4 v[0:1], off
	s_add_i32 m0, s61, 0x1c000
	v_lshl_add_u64 v[0:1], s[22:23], 0, v[178:179]
	global_load_lds_dwordx4 v[0:1], off
	v_lshl_add_u64 v[0:1], s[22:23], 0, v[182:183]
	s_add_i32 m0, s61, 0x1e000
	v_lshlrev_b32_e32 v2, 11, v197
	global_load_lds_dwordx4 v[0:1], off
	v_lshlrev_b32_e32 v1, 2, v189
	v_lshl_or_b32 v0, v189, 6, v190
	v_and_b32_e32 v1, 32, v1
	v_bitop3_b32 v0, v0, s9, v1 bitop3:0xde
	v_lshlrev_b32_e32 v1, 8, v192
	v_and_b32_e32 v1, 0x38000, v1
	v_or3_b32 v1, v186, v1, v2
	v_add_u32_e32 v128, v1, v187
	v_lshlrev_b32_e32 v1, 4, v198
	s_waitcnt vmcnt(6)
	s_cmpk_lt_u32 s20, 0x100
	v_and_b32_e32 v1, 0x78000, v1
	v_lshl_or_b32 v248, s21, 6, v189
	v_lshl_add_u32 v249, v188, 1, v189
	v_lshrrev_b32_e32 v250, 2, v249
	v_and_b32_e32 v251, 3, v249
	v_lshl_or_b32 v140, s21, 6, v250
	v_lshl_add_u32 v249, v251, 4, v250
	v_lshlrev_b32_e32 v249, 2, v249
	v_lshl_or_b32 v141, s24, 7, v191
	s_cselect_b64 s[20:21], -1, 0
	v_or3_b32 v1, v186, v1, v2
	s_add_i32 s68, 0, 0x10000
	s_add_i32 s69, 0, 0x14000
	v_lshl_or_b32 v142, v251, 3, s24
	v_mov_b32_e32 v129, v179
	v_add_u32_e32 v130, v1, v187
	v_mov_b32_e32 v131, v179
	v_add_u32_e32 v143, s68, v141
	v_add_u32_e32 v146, s69, v141
	v_add_u32_e32 v147, 0, v0
	s_movk_i32 s71, 0x2b00
	s_movk_i32 s72, 0x1580
	v_mov_b32_e32 v148, 0x358637bd
	s_mov_b32 s73, 0x800000
	s_barrier
	s_branch .LBB0_840

; template <class Epi, class Sched, bool ALIGN_EPI = false, bool SP2 = false>
; __device__ __forceinline__ void gemm_phase(PG8_LAS unsigned char* lds, const Gemm g, const Sched& S, const Epi& E) {
;     ...
; #pragma unroll
;     for (int a = 0; a < 2; ++a)
; #pragma unroll
;         for (int b = 0; b < 2; ++b)
; #pragma unroll
;             for (int m = 0; m < 4; ++m)
; #pragma unroll
;                 for (int n = 0; n < 2; ++n) acc[a][b][m][n] = (f32x4){0.f, 0.f, 0.f, 0.f};
.LBB0_842:
	s_ashr_i32 s23, s22, 31
	s_lshl_b64 s[26:27], s[22:23], 19
	s_add_u32 s26, s58, s26
	s_addc_u32 s27, s59, s27
	s_and_b64 s[38:39], s[36:37], exec
	s_cselect_b32 s9, s27, s3
	s_cselect_b32 s23, s26, s2
	s_ashr_i32 s25, s24, 31
	s_lshl_b64 s[38:39], s[24:25], 19
	s_add_u32 s38, s49, s38
	s_addc_u32 s39, s50, s39
	s_and_b64 s[44:45], s[36:37], exec
	s_cselect_b32 s25, s39, s43
	s_cselect_b32 s41, s38, s42
	s_add_u32 s2, s2, 0x40080
	s_addc_u32 s3, s3, 0
	s_add_u32 s74, s42, 0x100
	v_mov_b32_e32 v0, 0
	s_addc_u32 s75, s43, 0
	s_mov_b32 s76, -2
	v_mov_b32_e32 v1, v0
	v_mov_b32_e32 v2, v0
	v_mov_b32_e32 v3, v0
	v_mov_b32_e32 v4, v0
	v_mov_b32_e32 v5, v0
	v_mov_b32_e32 v6, v0
	v_mov_b32_e32 v7, v0
	v_mov_b32_e32 v16, v0
	v_mov_b32_e32 v17, v0
	v_mov_b32_e32 v18, v0
	v_mov_b32_e32 v19, v0
	v_mov_b32_e32 v20, v0
	v_mov_b32_e32 v21, v0
	v_mov_b32_e32 v22, v0
	v_mov_b32_e32 v23, v0
	v_mov_b32_e32 v32, v0
	v_mov_b32_e32 v33, v0
	v_mov_b32_e32 v34, v0
	v_mov_b32_e32 v35, v0
	v_mov_b32_e32 v36, v0
	v_mov_b32_e32 v37, v0
	v_mov_b32_e32 v38, v0
	v_mov_b32_e32 v39, v0
	v_mov_b32_e32 v48, v0
	v_mov_b32_e32 v49, v0
	v_mov_b32_e32 v50, v0
	v_mov_b32_e32 v51, v0
	v_mov_b32_e32 v52, v0
	v_mov_b32_e32 v53, v0
	v_mov_b32_e32 v54, v0
	v_mov_b32_e32 v55, v0
	v_mov_b32_e32 v8, v0
	v_mov_b32_e32 v9, v0
	v_mov_b32_e32 v10, v0
	v_mov_b32_e32 v11, v0
	v_mov_b32_e32 v12, v0
	v_mov_b32_e32 v13, v0
	v_mov_b32_e32 v14, v0
	v_mov_b32_e32 v15, v0
	v_mov_b32_e32 v24, v0
	v_mov_b32_e32 v25, v0
	v_mov_b32_e32 v26, v0
	v_mov_b32_e32 v27, v0
	v_mov_b32_e32 v28, v0
	v_mov_b32_e32 v29, v0
	v_mov_b32_e32 v30, v0
	v_mov_b32_e32 v31, v0
	v_mov_b32_e32 v40, v0
	v_mov_b32_e32 v41, v0
	v_mov_b32_e32 v42, v0
	v_mov_b32_e32 v43, v0
	v_mov_b32_e32 v44, v0
	v_mov_b32_e32 v45, v0
	v_mov_b32_e32 v46, v0
	v_mov_b32_e32 v47, v0
	v_mov_b32_e32 v56, v0
	v_mov_b32_e32 v57, v0
	v_mov_b32_e32 v58, v0
	v_mov_b32_e32 v59, v0
	v_mov_b32_e32 v60, v0
	v_mov_b32_e32 v61, v0
	v_mov_b32_e32 v62, v0
	v_mov_b32_e32 v63, v0
	v_mov_b32_e32 v64, v0
	v_mov_b32_e32 v65, v0
	v_mov_b32_e32 v66, v0
	v_mov_b32_e32 v67, v0
	v_mov_b32_e32 v68, v0
	v_mov_b32_e32 v69, v0
	v_mov_b32_e32 v70, v0
	v_mov_b32_e32 v71, v0
	v_mov_b32_e32 v80, v0
	v_mov_b32_e32 v81, v0
	v_mov_b32_e32 v82, v0
	v_mov_b32_e32 v83, v0
	v_mov_b32_e32 v84, v0
	v_mov_b32_e32 v85, v0
	v_mov_b32_e32 v86, v0
	v_mov_b32_e32 v87, v0
	v_mov_b32_e32 v96, v0
	v_mov_b32_e32 v97, v0
	v_mov_b32_e32 v98, v0
	v_mov_b32_e32 v99, v0
	v_mov_b32_e32 v100, v0
	v_mov_b32_e32 v101, v0
	v_mov_b32_e32 v102, v0
	v_mov_b32_e32 v103, v0
	v_mov_b32_e32 v112, v0
	v_mov_b32_e32 v113, v0
	v_mov_b32_e32 v114, v0
	v_mov_b32_e32 v115, v0
	v_mov_b32_e32 v116, v0
	v_mov_b32_e32 v117, v0
	v_mov_b32_e32 v118, v0
	v_mov_b32_e32 v119, v0
	v_mov_b32_e32 v72, v0
	v_mov_b32_e32 v73, v0
	v_mov_b32_e32 v74, v0
	v_mov_b32_e32 v75, v0
	v_mov_b32_e32 v76, v0
	v_mov_b32_e32 v77, v0
	v_mov_b32_e32 v78, v0
	v_mov_b32_e32 v79, v0
	v_mov_b32_e32 v88, v0
	v_mov_b32_e32 v89, v0
	v_mov_b32_e32 v90, v0
	v_mov_b32_e32 v91, v0
	v_mov_b32_e32 v92, v0
	v_mov_b32_e32 v93, v0
	v_mov_b32_e32 v94, v0
	v_mov_b32_e32 v95, v0
	v_mov_b32_e32 v104, v0
	v_mov_b32_e32 v105, v0
	v_mov_b32_e32 v106, v0
	v_mov_b32_e32 v107, v0
	v_mov_b32_e32 v108, v0
	v_mov_b32_e32 v109, v0
	v_mov_b32_e32 v110, v0
	v_mov_b32_e32 v111, v0
	v_mov_b32_e32 v120, v0
	v_mov_b32_e32 v121, v0
	v_mov_b32_e32 v122, v0
	v_mov_b32_e32 v123, v0
	v_mov_b32_e32 v124, v0
	v_mov_b32_e32 v125, v0
	v_mov_b32_e32 v126, v0
	v_mov_b32_e32 v127, v0
	v_lshl_add_u32 v238, s40, 8, v248
	v_ashrrev_i32_e32 v239, 31, v238
	v_lshl_add_u64 v[238:239], v[238:239], 2, s[16:17]
	global_load_dword v240, v[238:239], off
	global_load_dword v241, v[238:239], off offset:64
	global_load_dword v242, v[238:239], off offset:128
	global_load_dword v243, v[238:239], off offset:192
	global_load_dword v244, v[238:239], off offset:512
	global_load_dword v245, v[238:239], off offset:576
	global_load_dword v246, v[238:239], off offset:640
	global_load_dword v247, v[238:239], off offset:704

;     DI void operator()(const f32x4 (&acc)[2][2][4][2], const Unit& u, int wr, int wc, int fr, int fq) const {
; #pragma unroll
;         for (int ai = 0; ai < 2; ++ai)
; #pragma unroll
;             for (int m = 0; m < 4; ++m) {
;                 const int r = u.pm * BM + ai * HALF + wr * 64 + m * 16 + fr;
; #pragma unroll
;                 for (int bj = 0; bj < 2; ++bj) f(r, u.pn * BM + bj * HALF + wc * 32 + 8 * fq, acc[ai][bj][m][0], acc[ai][bj][m][1]);
;                 asm volatile("" ::: "memory");
;             }
.LBB0_846:
	v_lshl_add_u32 v134, s40, 8, v140
	v_lshl_or_b32 v132, s8, 8, v142
	v_ashrrev_i32_e32 v135, 31, v134
	v_mad_i64_i32 v[136:137], s[2:3], v134, s71, 0
	v_cmp_gt_i32_e32 vcc, s72, v132
	v_lshl_add_u64 v[136:137], s[10:11], 0, v[136:137]
	v_ashrrev_i32_e32 v133, 31, v132
	v_lshl_add_u64 v[138:139], v[134:135], 2, s[16:17]
	s_and_saveexec_b64 s[8:9], vcc
	s_cbranch_execz .LBB0_848
	v_mov_b32_e32 v135, v240
	v_lshl_add_u64 v[150:151], v[132:133], 1, v[136:137]
	v_fmamk_f32 v135, v135, 0x3a800000, v148
	v_mul_f32_e32 v149, 0x4b800000, v135
	v_cmp_gt_f32_e64 s[2:3], s73, v135
	s_nop 1
	v_cndmask_b32_e64 v135, v135, v149, s[2:3]
	v_rsq_f32_e32 v135, v135
	s_nop 0
	v_mul_f32_e32 v149, 0x45800000, v135
	v_cndmask_b32_e64 v152, v135, v149, s[2:3]
	v_pk_mul_f32 v[126:127], v[126:127], v[152:153] op_sel_hi:[1,0]
	v_pk_mul_f32 v[124:125], v[124:125], v[152:153] op_sel_hi:[1,0]
	v_pk_mul_f32 v[154:155], v[122:123], v[152:153] op_sel_hi:[1,0]
	v_pk_mul_f32 v[122:123], v[120:121], v[152:153] op_sel_hi:[1,0]
	v_cvt_pk_bf16_f32 v120, v124, v125
	v_cvt_pk_bf16_f32 v121, v126, v127
	v_cvt_pk_bf16_f32 v122, v122, v123
	v_cvt_pk_bf16_f32 v123, v154, v155
	ds_bpermute_b32 v120, v249, v120
	ds_bpermute_b32 v121, v249, v121
	ds_bpermute_b32 v122, v249, v122
	ds_bpermute_b32 v123, v249, v123
	s_waitcnt lgkmcnt(0)
	global_store_dwordx4 v[150:151], v[120:123], off
.LBB0_848:
	s_or_b64 exec, exec, s[8:9]
	s_nop 0
	v_or_b32_e32 v120, 0x80, v132
	v_cmp_gt_i32_e64 s[2:3], s72, v120
	s_and_saveexec_b64 s[40:41], s[2:3]
	s_cbranch_execz .LBB0_850
	v_mov_b32_e32 v120, v240
	v_fmamk_f32 v120, v120, 0x3a800000, v148
	v_mul_f32_e32 v121, 0x4b800000, v120
	v_cmp_gt_f32_e64 s[8:9], s73, v120
	s_nop 1
	v_cndmask_b32_e64 v120, v120, v121, s[8:9]
	v_rsq_f32_e32 v122, v120
	v_lshl_add_u64 v[120:121], v[132:133], 1, v[136:137]
	v_mul_f32_e32 v123, 0x45800000, v122
	v_cndmask_b32_e64 v122, v122, v123, s[8:9]
	v_pk_mul_f32 v[118:119], v[118:119], v[122:123] op_sel_hi:[1,0]
	v_pk_mul_f32 v[116:117], v[116:117], v[122:123] op_sel_hi:[1,0]
	v_pk_mul_f32 v[124:125], v[114:115], v[122:123] op_sel_hi:[1,0]
	v_pk_mul_f32 v[114:115], v[112:113], v[122:123] op_sel_hi:[1,0]
	v_cvt_pk_bf16_f32 v112, v116, v117
	v_cvt_pk_bf16_f32 v113, v118, v119
	v_cvt_pk_bf16_f32 v114, v114, v115
	v_cvt_pk_bf16_f32 v115, v124, v125
	ds_bpermute_b32 v112, v249, v112
	ds_bpermute_b32 v113, v249, v113
	ds_bpermute_b32 v114, v249, v114
	ds_bpermute_b32 v115, v249, v115
	s_waitcnt lgkmcnt(0)
	global_store_dwordx4 v[120:121], v[112:115], off offset:256
.LBB0_850:
	s_or_b64 exec, exec, s[40:41]
	s_nop 0
	v_or_b32_e32 v114, 16, v134
	v_ashrrev_i32_e32 v115, 31, v114
	v_mad_i64_i32 v[112:113], s[8:9], v114, s71, 0
	v_lshl_add_u64 v[112:113], s[10:11], 0, v[112:113]
	v_lshl_add_u64 v[114:115], v[114:115], 2, s[16:17]
	s_and_saveexec_b64 s[40:41], vcc
	s_cbranch_execz .LBB0_852
	v_mov_b32_e32 v116, v241
	v_fmamk_f32 v116, v116, 0x3a800000, v148
	v_mul_f32_e32 v117, 0x4b800000, v116
	v_cmp_gt_f32_e64 s[8:9], s73, v116
	s_nop 1
	v_cndmask_b32_e64 v116, v116, v117, s[8:9]
	v_rsq_f32_e32 v118, v116
	v_lshl_add_u64 v[116:117], v[132:133], 1, v[112:113]
	v_mul_f32_e32 v119, 0x45800000, v118
	v_cndmask_b32_e64 v118, v118, v119, s[8:9]
	v_pk_mul_f32 v[110:111], v[110:111], v[118:119] op_sel_hi:[1,0]
	v_pk_mul_f32 v[108:109], v[108:109], v[118:119] op_sel_hi:[1,0]
	v_pk_mul_f32 v[120:121], v[106:107], v[118:119] op_sel_hi:[1,0]
	v_pk_mul_f32 v[106:107], v[104:105], v[118:119] op_sel_hi:[1,0]
	v_cvt_pk_bf16_f32 v104, v108, v109
	v_cvt_pk_bf16_f32 v105, v110, v111
	v_cvt_pk_bf16_f32 v106, v106, v107
	v_cvt_pk_bf16_f32 v107, v120, v121
	ds_bpermute_b32 v104, v249, v104
	ds_bpermute_b32 v105, v249, v105
	ds_bpermute_b32 v106, v249, v106
	ds_bpermute_b32 v107, v249, v107
	s_waitcnt lgkmcnt(0)
	global_store_dwordx4 v[116:117], v[104:107], off
.LBB0_852:
	s_or_b64 exec, exec, s[40:41]
	s_and_saveexec_b64 s[40:41], s[2:3]
	s_cbranch_execz .LBB0_854
	v_mov_b32_e32 v104, v241
	v_fmamk_f32 v104, v104, 0x3a800000, v148
	v_mul_f32_e32 v105, 0x4b800000, v104
	v_cmp_gt_f32_e64 s[8:9], s73, v104
	s_nop 1
	v_cndmask_b32_e64 v104, v104, v105, s[8:9]
	v_rsq_f32_e32 v106, v104
	v_lshl_add_u64 v[104:105], v[132:133], 1, v[112:113]
	v_mul_f32_e32 v107, 0x45800000, v106
	v_cndmask_b32_e64 v106, v106, v107, s[8:9]
	v_pk_mul_f32 v[102:103], v[102:103], v[106:107] op_sel_hi:[1,0]
	v_pk_mul_f32 v[100:101], v[100:101], v[106:107] op_sel_hi:[1,0]
	v_pk_mul_f32 v[108:109], v[98:99], v[106:107] op_sel_hi:[1,0]
	v_pk_mul_f32 v[98:99], v[96:97], v[106:107] op_sel_hi:[1,0]
	v_cvt_pk_bf16_f32 v96, v100, v101
	v_cvt_pk_bf16_f32 v97, v102, v103
	v_cvt_pk_bf16_f32 v98, v98, v99
	v_cvt_pk_bf16_f32 v99, v108, v109
	ds_bpermute_b32 v96, v249, v96
	ds_bpermute_b32 v97, v249, v97
	ds_bpermute_b32 v98, v249, v98
	ds_bpermute_b32 v99, v249, v99
	s_waitcnt lgkmcnt(0)
	global_store_dwordx4 v[104:105], v[96:99], off offset:256
.LBB0_854:
	s_or_b64 exec, exec, s[40:41]
	s_nop 0
	v_or_b32_e32 v98, 32, v134
	v_ashrrev_i32_e32 v99, 31, v98
	v_mad_i64_i32 v[96:97], s[8:9], v98, s71, 0
	v_lshl_add_u64 v[96:97], s[10:11], 0, v[96:97]
	v_lshl_add_u64 v[98:99], v[98:99], 2, s[16:17]
	s_and_saveexec_b64 s[40:41], vcc
	s_cbranch_execz .LBB0_856
	v_mov_b32_e32 v100, v242
	v_fmamk_f32 v100, v100, 0x3a800000, v148
	v_mul_f32_e32 v101, 0x4b800000, v100
	v_cmp_gt_f32_e64 s[8:9], s73, v100
	s_nop 1
	v_cndmask_b32_e64 v100, v100, v101, s[8:9]
	v_rsq_f32_e32 v102, v100
	v_lshl_add_u64 v[100:101], v[132:133], 1, v[96:97]
	v_mul_f32_e32 v103, 0x45800000, v102
	v_cndmask_b32_e64 v102, v102, v103, s[8:9]
	v_pk_mul_f32 v[94:95], v[94:95], v[102:103] op_sel_hi:[1,0]
	v_pk_mul_f32 v[92:93], v[92:93], v[102:103] op_sel_hi:[1,0]
	v_pk_mul_f32 v[104:105], v[90:91], v[102:103] op_sel_hi:[1,0]
	v_pk_mul_f32 v[90:91], v[88:89], v[102:103] op_sel_hi:[1,0]
	v_cvt_pk_bf16_f32 v88, v92, v93
	v_cvt_pk_bf16_f32 v89, v94, v95
	v_cvt_pk_bf16_f32 v90, v90, v91
	v_cvt_pk_bf16_f32 v91, v104, v105
	ds_bpermute_b32 v88, v249, v88
	ds_bpermute_b32 v89, v249, v89
	ds_bpermute_b32 v90, v249, v90
	ds_bpermute_b32 v91, v249, v91
	s_waitcnt lgkmcnt(0)
	global_store_dwordx4 v[100:101], v[88:91], off
;     DI void operator()(const f32x4 (&acc)[2][2][4][2], const Unit& u, int wr, int wc, int fr, int fq) const {
; #pragma unroll
;         for (int ai = 0; ai < 2; ++ai)
; #pragma unroll
;             for (int m = 0; m < 4; ++m) {
;                 const int r = u.pm * BM + ai * HALF + wr * 64 + m * 16 + fr;
; #pragma unroll
;                 for (int bj = 0; bj < 2; ++bj) f(r, u.pn * BM + bj * HALF + wc * 32 + 8 * fq, acc[ai][bj][m][0], acc[ai][bj][m][1]);
;                 asm volatile("" ::: "memory");
;             }
.LBB0_856:
	s_or_b64 exec, exec, s[40:41]
	s_and_saveexec_b64 s[40:41], s[2:3]
	s_cbranch_execz .LBB0_858
	v_mov_b32_e32 v88, v242
	v_fmamk_f32 v88, v88, 0x3a800000, v148
	v_mul_f32_e32 v89, 0x4b800000, v88
	v_cmp_gt_f32_e64 s[8:9], s73, v88
	s_nop 1
	v_cndmask_b32_e64 v88, v88, v89, s[8:9]
	v_rsq_f32_e32 v90, v88
	v_lshl_add_u64 v[88:89], v[132:133], 1, v[96:97]
	v_mul_f32_e32 v91, 0x45800000, v90
	v_cndmask_b32_e64 v90, v90, v91, s[8:9]
	v_pk_mul_f32 v[86:87], v[86:87], v[90:91] op_sel_hi:[1,0]
	v_pk_mul_f32 v[84:85], v[84:85], v[90:91] op_sel_hi:[1,0]
	v_pk_mul_f32 v[92:93], v[82:83], v[90:91] op_sel_hi:[1,0]
	v_pk_mul_f32 v[82:83], v[80:81], v[90:91] op_sel_hi:[1,0]
	v_cvt_pk_bf16_f32 v80, v84, v85
	v_cvt_pk_bf16_f32 v81, v86, v87
	v_cvt_pk_bf16_f32 v82, v82, v83
	v_cvt_pk_bf16_f32 v83, v92, v93
	ds_bpermute_b32 v80, v249, v80
	ds_bpermute_b32 v81, v249, v81
	ds_bpermute_b32 v82, v249, v82
	ds_bpermute_b32 v83, v249, v83
	s_waitcnt lgkmcnt(0)
	global_store_dwordx4 v[88:89], v[80:83], off offset:256
.LBB0_858:
	s_or_b64 exec, exec, s[40:41]
	s_nop 0
	v_or_b32_e32 v82, 48, v134
	v_ashrrev_i32_e32 v83, 31, v82
	v_mad_i64_i32 v[80:81], s[8:9], v82, s71, 0
	v_lshl_add_u64 v[80:81], s[10:11], 0, v[80:81]
	v_lshl_add_u64 v[82:83], v[82:83], 2, s[16:17]
	s_and_saveexec_b64 s[40:41], vcc
	s_cbranch_execz .LBB0_860
	v_mov_b32_e32 v84, v243
	v_fmamk_f32 v84, v84, 0x3a800000, v148
	v_mul_f32_e32 v85, 0x4b800000, v84
	v_cmp_gt_f32_e64 s[8:9], s73, v84
	s_nop 1
	v_cndmask_b32_e64 v84, v84, v85, s[8:9]
	v_rsq_f32_e32 v86, v84
	v_lshl_add_u64 v[84:85], v[132:133], 1, v[80:81]
	v_mul_f32_e32 v87, 0x45800000, v86
	v_cndmask_b32_e64 v86, v86, v87, s[8:9]
	v_pk_mul_f32 v[78:79], v[78:79], v[86:87] op_sel_hi:[1,0]
	v_pk_mul_f32 v[76:77], v[76:77], v[86:87] op_sel_hi:[1,0]
	v_pk_mul_f32 v[88:89], v[74:75], v[86:87] op_sel_hi:[1,0]
	v_pk_mul_f32 v[74:75], v[72:73], v[86:87] op_sel_hi:[1,0]
	v_cvt_pk_bf16_f32 v72, v76, v77
	v_cvt_pk_bf16_f32 v73, v78, v79
	v_cvt_pk_bf16_f32 v74, v74, v75
	v_cvt_pk_bf16_f32 v75, v88, v89
	ds_bpermute_b32 v72, v249, v72
	ds_bpermute_b32 v73, v249, v73
	ds_bpermute_b32 v74, v249, v74
	ds_bpermute_b32 v75, v249, v75
	s_waitcnt lgkmcnt(0)
	global_store_dwordx4 v[84:85], v[72:75], off
.LBB0_860:
	s_or_b64 exec, exec, s[40:41]
	s_and_saveexec_b64 s[40:41], s[2:3]
	s_cbranch_execz .LBB0_862
	v_mov_b32_e32 v72, v243
	v_fmamk_f32 v72, v72, 0x3a800000, v148
	v_mul_f32_e32 v73, 0x4b800000, v72
	v_cmp_gt_f32_e64 s[8:9], s73, v72
	s_nop 1
	v_cndmask_b32_e64 v72, v72, v73, s[8:9]
	v_rsq_f32_e32 v74, v72
	v_lshl_add_u64 v[72:73], v[132:133], 1, v[80:81]
	v_mul_f32_e32 v75, 0x45800000, v74
	v_cndmask_b32_e64 v74, v74, v75, s[8:9]
	v_pk_mul_f32 v[70:71], v[70:71], v[74:75] op_sel_hi:[1,0]
	v_pk_mul_f32 v[68:69], v[68:69], v[74:75] op_sel_hi:[1,0]
	v_pk_mul_f32 v[76:77], v[66:67], v[74:75] op_sel_hi:[1,0]
	v_pk_mul_f32 v[66:67], v[64:65], v[74:75] op_sel_hi:[1,0]
	v_cvt_pk_bf16_f32 v64, v68, v69
	v_cvt_pk_bf16_f32 v65, v70, v71
	v_cvt_pk_bf16_f32 v66, v66, v67
	v_cvt_pk_bf16_f32 v67, v76, v77
	ds_bpermute_b32 v64, v249, v64
	ds_bpermute_b32 v65, v249, v65
	ds_bpermute_b32 v66, v249, v66
	ds_bpermute_b32 v67, v249, v67
	s_waitcnt lgkmcnt(0)
	global_store_dwordx4 v[72:73], v[64:67], off offset:256
.LBB0_862:
	s_or_b64 exec, exec, s[40:41]
	s_nop 0
	v_add_u32_e32 v66, 0x80, v134
	v_ashrrev_i32_e32 v67, 31, v66
	v_mad_i64_i32 v[64:65], s[8:9], v66, s71, 0
	v_lshl_add_u64 v[64:65], s[10:11], 0, v[64:65]
	v_lshl_add_u64 v[66:67], v[66:67], 2, s[16:17]
	s_and_saveexec_b64 s[40:41], vcc
	s_cbranch_execz .LBB0_864
	v_mov_b32_e32 v68, v244
	v_fmamk_f32 v68, v68, 0x3a800000, v148
	v_mul_f32_e32 v69, 0x4b800000, v68
	v_cmp_gt_f32_e64 s[8:9], s73, v68
	s_nop 1
	v_cndmask_b32_e64 v68, v68, v69, s[8:9]
	v_rsq_f32_e32 v70, v68
	v_lshl_add_u64 v[68:69], v[132:133], 1, v[64:65]
	v_mul_f32_e32 v71, 0x45800000, v70
	v_cndmask_b32_e64 v70, v70, v71, s[8:9]
	v_pk_mul_f32 v[62:63], v[62:63], v[70:71] op_sel_hi:[1,0]
	v_pk_mul_f32 v[60:61], v[60:61], v[70:71] op_sel_hi:[1,0]
	v_pk_mul_f32 v[72:73], v[58:59], v[70:71] op_sel_hi:[1,0]
	v_pk_mul_f32 v[58:59], v[56:57], v[70:71] op_sel_hi:[1,0]
	v_cvt_pk_bf16_f32 v56, v60, v61
	v_cvt_pk_bf16_f32 v57, v62, v63
	v_cvt_pk_bf16_f32 v58, v58, v59
	v_cvt_pk_bf16_f32 v59, v72, v73
	ds_bpermute_b32 v56, v249, v56
	ds_bpermute_b32 v57, v249, v57
	ds_bpermute_b32 v58, v249, v58
	ds_bpermute_b32 v59, v249, v59
	s_waitcnt lgkmcnt(0)
	global_store_dwordx4 v[68:69], v[56:59], off
.LBB0_864:
	s_or_b64 exec, exec, s[40:41]
	s_and_saveexec_b64 s[40:41], s[2:3]
	s_cbranch_execz .LBB0_866
	v_mov_b32_e32 v56, v244
	v_fmamk_f32 v56, v56, 0x3a800000, v148
	v_mul_f32_e32 v57, 0x4b800000, v56
	v_cmp_gt_f32_e64 s[8:9], s73, v56
	s_nop 1
	v_cndmask_b32_e64 v56, v56, v57, s[8:9]
	v_rsq_f32_e32 v58, v56
	v_lshl_add_u64 v[56:57], v[132:133], 1, v[64:65]
	v_mul_f32_e32 v59, 0x45800000, v58
	v_cndmask_b32_e64 v58, v58, v59, s[8:9]
	v_pk_mul_f32 v[54:55], v[54:55], v[58:59] op_sel_hi:[1,0]
	v_pk_mul_f32 v[52:53], v[52:53], v[58:59] op_sel_hi:[1,0]
	v_pk_mul_f32 v[60:61], v[50:51], v[58:59] op_sel_hi:[1,0]
	v_pk_mul_f32 v[50:51], v[48:49], v[58:59] op_sel_hi:[1,0]
	v_cvt_pk_bf16_f32 v48, v52, v53
	v_cvt_pk_bf16_f32 v49, v54, v55
	v_cvt_pk_bf16_f32 v50, v50, v51
	v_cvt_pk_bf16_f32 v51, v60, v61
	ds_bpermute_b32 v48, v249, v48
	ds_bpermute_b32 v49, v249, v49
	ds_bpermute_b32 v50, v249, v50
	ds_bpermute_b32 v51, v249, v51
	s_waitcnt lgkmcnt(0)
	global_store_dwordx4 v[56:57], v[48:51], off offset:256
;     DI void operator()(const f32x4 (&acc)[2][2][4][2], const Unit& u, int wr, int wc, int fr, int fq) const {
; #pragma unroll
;         for (int ai = 0; ai < 2; ++ai)
; #pragma unroll
;             for (int m = 0; m < 4; ++m) {
;                 const int r = u.pm * BM + ai * HALF + wr * 64 + m * 16 + fr;
; #pragma unroll
;                 for (int bj = 0; bj < 2; ++bj) f(r, u.pn * BM + bj * HALF + wc * 32 + 8 * fq, acc[ai][bj][m][0], acc[ai][bj][m][1]);
;                 asm volatile("" ::: "memory");
;             }
.LBB0_866:
	s_or_b64 exec, exec, s[40:41]
	s_nop 0
	v_add_u32_e32 v50, 0x90, v134
	v_ashrrev_i32_e32 v51, 31, v50
	v_mad_i64_i32 v[48:49], s[8:9], v50, s71, 0
	v_lshl_add_u64 v[48:49], s[10:11], 0, v[48:49]
	v_lshl_add_u64 v[50:51], v[50:51], 2, s[16:17]
	s_and_saveexec_b64 s[40:41], vcc
	s_cbranch_execz .LBB0_868
	v_mov_b32_e32 v52, v245
	v_fmamk_f32 v52, v52, 0x3a800000, v148
	v_mul_f32_e32 v53, 0x4b800000, v52
	v_cmp_gt_f32_e64 s[8:9], s73, v52
	s_nop 1
	v_cndmask_b32_e64 v52, v52, v53, s[8:9]
	v_rsq_f32_e32 v54, v52
	v_lshl_add_u64 v[52:53], v[132:133], 1, v[48:49]
	v_mul_f32_e32 v55, 0x45800000, v54
	v_cndmask_b32_e64 v54, v54, v55, s[8:9]
	v_pk_mul_f32 v[46:47], v[46:47], v[54:55] op_sel_hi:[1,0]
	v_pk_mul_f32 v[44:45], v[44:45], v[54:55] op_sel_hi:[1,0]
	v_pk_mul_f32 v[56:57], v[42:43], v[54:55] op_sel_hi:[1,0]
	v_pk_mul_f32 v[42:43], v[40:41], v[54:55] op_sel_hi:[1,0]
	v_cvt_pk_bf16_f32 v40, v44, v45
	v_cvt_pk_bf16_f32 v41, v46, v47
	v_cvt_pk_bf16_f32 v42, v42, v43
	v_cvt_pk_bf16_f32 v43, v56, v57
	ds_bpermute_b32 v40, v249, v40
	ds_bpermute_b32 v41, v249, v41
	ds_bpermute_b32 v42, v249, v42
	ds_bpermute_b32 v43, v249, v43
	s_waitcnt lgkmcnt(0)
	global_store_dwordx4 v[52:53], v[40:43], off
.LBB0_868:
	s_or_b64 exec, exec, s[40:41]
	s_and_saveexec_b64 s[40:41], s[2:3]
	s_cbranch_execz .LBB0_870
	v_mov_b32_e32 v40, v245
	v_fmamk_f32 v40, v40, 0x3a800000, v148
	v_mul_f32_e32 v41, 0x4b800000, v40
	v_cmp_gt_f32_e64 s[8:9], s73, v40
	s_nop 1
	v_cndmask_b32_e64 v40, v40, v41, s[8:9]
	v_rsq_f32_e32 v42, v40
	v_lshl_add_u64 v[40:41], v[132:133], 1, v[48:49]
	v_mul_f32_e32 v43, 0x45800000, v42
	v_cndmask_b32_e64 v42, v42, v43, s[8:9]
	v_pk_mul_f32 v[38:39], v[38:39], v[42:43] op_sel_hi:[1,0]
	v_pk_mul_f32 v[36:37], v[36:37], v[42:43] op_sel_hi:[1,0]
	v_pk_mul_f32 v[44:45], v[34:35], v[42:43] op_sel_hi:[1,0]
	v_pk_mul_f32 v[34:35], v[32:33], v[42:43] op_sel_hi:[1,0]
	v_cvt_pk_bf16_f32 v32, v36, v37
	v_cvt_pk_bf16_f32 v33, v38, v39
	v_cvt_pk_bf16_f32 v34, v34, v35
	v_cvt_pk_bf16_f32 v35, v44, v45
	ds_bpermute_b32 v32, v249, v32
	ds_bpermute_b32 v33, v249, v33
	ds_bpermute_b32 v34, v249, v34
	ds_bpermute_b32 v35, v249, v35
	s_waitcnt lgkmcnt(0)
	global_store_dwordx4 v[40:41], v[32:35], off offset:256
.LBB0_870:
	s_or_b64 exec, exec, s[40:41]
	s_nop 0
	v_add_u32_e32 v34, 0xa0, v134
	v_ashrrev_i32_e32 v35, 31, v34
	v_mad_i64_i32 v[32:33], s[8:9], v34, s71, 0
	v_lshl_add_u64 v[32:33], s[10:11], 0, v[32:33]
	v_lshl_add_u64 v[34:35], v[34:35], 2, s[16:17]
	s_and_saveexec_b64 s[40:41], vcc
	s_cbranch_execz .LBB0_872
	v_mov_b32_e32 v36, v246
	v_fmamk_f32 v36, v36, 0x3a800000, v148
	v_mul_f32_e32 v37, 0x4b800000, v36
	v_cmp_gt_f32_e64 s[8:9], s73, v36
	s_nop 1
	v_cndmask_b32_e64 v36, v36, v37, s[8:9]
	v_rsq_f32_e32 v38, v36
	v_lshl_add_u64 v[36:37], v[132:133], 1, v[32:33]
	v_mul_f32_e32 v39, 0x45800000, v38
	v_cndmask_b32_e64 v38, v38, v39, s[8:9]
	v_pk_mul_f32 v[30:31], v[30:31], v[38:39] op_sel_hi:[1,0]
	v_pk_mul_f32 v[28:29], v[28:29], v[38:39] op_sel_hi:[1,0]
	v_pk_mul_f32 v[40:41], v[26:27], v[38:39] op_sel_hi:[1,0]
	v_pk_mul_f32 v[26:27], v[24:25], v[38:39] op_sel_hi:[1,0]
	v_cvt_pk_bf16_f32 v24, v28, v29
	v_cvt_pk_bf16_f32 v25, v30, v31
	v_cvt_pk_bf16_f32 v26, v26, v27
	v_cvt_pk_bf16_f32 v27, v40, v41
	ds_bpermute_b32 v24, v249, v24
	ds_bpermute_b32 v25, v249, v25
	ds_bpermute_b32 v26, v249, v26
	ds_bpermute_b32 v27, v249, v27
	s_waitcnt lgkmcnt(0)
	global_store_dwordx4 v[36:37], v[24:27], off
.LBB0_872:
	s_or_b64 exec, exec, s[40:41]
	s_and_saveexec_b64 s[40:41], s[2:3]
	s_cbranch_execz .LBB0_874
	v_mov_b32_e32 v24, v246
	v_fmamk_f32 v24, v24, 0x3a800000, v148
	v_mul_f32_e32 v25, 0x4b800000, v24
	v_cmp_gt_f32_e64 s[8:9], s73, v24
	s_nop 1
	v_cndmask_b32_e64 v24, v24, v25, s[8:9]
	v_rsq_f32_e32 v26, v24
	v_lshl_add_u64 v[24:25], v[132:133], 1, v[32:33]
	v_mul_f32_e32 v27, 0x45800000, v26
	v_cndmask_b32_e64 v26, v26, v27, s[8:9]
	v_pk_mul_f32 v[22:23], v[22:23], v[26:27] op_sel_hi:[1,0]
	v_pk_mul_f32 v[20:21], v[20:21], v[26:27] op_sel_hi:[1,0]
	v_pk_mul_f32 v[28:29], v[18:19], v[26:27] op_sel_hi:[1,0]
	v_pk_mul_f32 v[18:19], v[16:17], v[26:27] op_sel_hi:[1,0]
	v_cvt_pk_bf16_f32 v16, v20, v21
	v_cvt_pk_bf16_f32 v17, v22, v23
	v_cvt_pk_bf16_f32 v18, v18, v19
	v_cvt_pk_bf16_f32 v19, v28, v29
	ds_bpermute_b32 v16, v249, v16
	ds_bpermute_b32 v17, v249, v17
	ds_bpermute_b32 v18, v249, v18
	ds_bpermute_b32 v19, v249, v19
	s_waitcnt lgkmcnt(0)
	global_store_dwordx4 v[24:25], v[16:19], off offset:256
.LBB0_874:
	s_or_b64 exec, exec, s[40:41]
	s_nop 0
	v_add_u32_e32 v18, 0xb0, v134
	v_ashrrev_i32_e32 v19, 31, v18
	v_mad_i64_i32 v[16:17], s[8:9], v18, s71, 0
	v_lshl_add_u64 v[16:17], s[10:11], 0, v[16:17]
	v_lshl_add_u64 v[18:19], v[18:19], 2, s[16:17]
	s_and_saveexec_b64 s[8:9], vcc
	s_cbranch_execz .LBB0_876
	v_mov_b32_e32 v20, v247
	v_fmamk_f32 v20, v20, 0x3a800000, v148
	v_mul_f32_e32 v21, 0x4b800000, v20
	v_cmp_gt_f32_e32 vcc, s73, v20
	s_nop 1
	v_cndmask_b32_e32 v20, v20, v21, vcc
	v_rsq_f32_e32 v22, v20
	v_lshl_add_u64 v[20:21], v[132:133], 1, v[16:17]
	v_mul_f32_e32 v23, 0x45800000, v22
	v_cndmask_b32_e32 v22, v22, v23, vcc
	v_pk_mul_f32 v[14:15], v[14:15], v[22:23] op_sel_hi:[1,0]
	v_pk_mul_f32 v[12:13], v[12:13], v[22:23] op_sel_hi:[1,0]
	v_pk_mul_f32 v[24:25], v[10:11], v[22:23] op_sel_hi:[1,0]
	v_pk_mul_f32 v[10:11], v[8:9], v[22:23] op_sel_hi:[1,0]
	v_cvt_pk_bf16_f32 v8, v12, v13
	v_cvt_pk_bf16_f32 v9, v14, v15
	v_cvt_pk_bf16_f32 v10, v10, v11
	v_cvt_pk_bf16_f32 v11, v24, v25
	ds_bpermute_b32 v8, v249, v8
	ds_bpermute_b32 v9, v249, v9
	ds_bpermute_b32 v10, v249, v10
	ds_bpermute_b32 v11, v249, v11
	s_waitcnt lgkmcnt(0)
	global_store_dwordx4 v[20:21], v[8:11], off
.LBB0_876:
	s_or_b64 exec, exec, s[8:9]
	s_and_saveexec_b64 s[8:9], s[2:3]
	s_cbranch_execz .LBB0_878
	v_mov_b32_e32 v8, v247
	v_fmamk_f32 v8, v8, 0x3a800000, v148
	v_mul_f32_e32 v9, 0x4b800000, v8
	v_cmp_gt_f32_e32 vcc, s73, v8
	s_nop 1
	v_cndmask_b32_e32 v8, v8, v9, vcc
	v_rsq_f32_e32 v10, v8
	v_lshl_add_u64 v[8:9], v[132:133], 1, v[16:17]
	v_mul_f32_e32 v11, 0x45800000, v10
	v_cndmask_b32_e32 v10, v10, v11, vcc
	v_pk_mul_f32 v[6:7], v[6:7], v[10:11] op_sel_hi:[1,0]
	v_pk_mul_f32 v[4:5], v[4:5], v[10:11] op_sel_hi:[1,0]
	v_pk_mul_f32 v[12:13], v[2:3], v[10:11] op_sel_hi:[1,0]
	v_pk_mul_f32 v[2:3], v[0:1], v[10:11] op_sel_hi:[1,0]
	v_cvt_pk_bf16_f32 v0, v4, v5
	v_cvt_pk_bf16_f32 v1, v6, v7
	v_cvt_pk_bf16_f32 v2, v2, v3
	v_cvt_pk_bf16_f32 v3, v12, v13
	ds_bpermute_b32 v0, v249, v0
	ds_bpermute_b32 v1, v249, v1
	ds_bpermute_b32 v2, v249, v2
	ds_bpermute_b32 v3, v249, v3
	s_waitcnt lgkmcnt(0)
	global_store_dwordx4 v[8:9], v[0:3], off offset:256
